# MLA / SWA / memory cross-attention unit epilogues: row-fragment stores widened to dwordx4 via v_permlane32_swap (T21), on top of the diff epilogue
# speedup vs baseline: 1.0063x; 1.0021x over previous
; __device__ __forceinline__ unsigned pk2(float lo, float hi) { f32x2 v = {lo, hi}; bf16x2_t b = __builtin_convertvector(v, bf16x2_t); return __builtin_bit_cast(unsigned, b); }
; __device__ __forceinline__ float shfl_xor_l(float v, int o, int lane) { return __builtin_bit_cast(float, __builtin_amdgcn_ds_bpermute((lane ^ o) << 2, __builtin_bit_cast(int, v))); }
; template <int DQK, int DV, int FLAGS, int qp, int kp, int vts, int op> ...
;     ...
;     float lt = l + shfl_xor_l(l, 32, lane);
;     if (FLAGS & AF_SINK) lt += __builtin_amdgcn_exp2f(sink2 - m);
;     const float inv = 1.0f / lt;
;     bf16* orow = O + (size_t)(32 * wave + r32) * op + 4 * hi;
; #pragma unroll
;     for (int d = 0; d < NDB; ++d)
; #pragma unroll
;         for (int g = 0; g < 4; ++g) {
;             u32x2 w; w.x = pk2(o[d][4 * g] * inv, o[d][4 * g + 1] * inv); w.y = pk2(o[d][4 * g + 2] * inv, o[d][4 * g + 3] * inv);
;             *(u32x2*)(orow + 32 * d + 8 * g) = w;
;         }
; __global__ void __launch_bounds__(NTHREADS, 2) mega_fwd(Args args) {
;     ...
;         for (int j = bid; j < 1024; j += G) {
.LBB0_525:
	ds_bpermute_b32 v0, v48, v175
	s_lshl_b32 s2, s86, 6
	s_lshl_b64 s[8:9], s[84:85], 11
	s_add_u32 s3, s74, s8
	s_addc_u32 s10, s75, s9
	s_waitcnt lgkmcnt(0)
	v_add_f32_e32 v0, v175, v0
	v_div_scale_f32 v2, s[8:9], v0, v0, 1.0
	v_rcp_f32_e32 v3, v2
	s_lshl_b32 s2, s2, 1
	v_ashrrev_i32_e32 v169, 31, v168
	s_add_u32 s2, s3, s2
	v_fma_f32 v4, -v2, v3, 1.0
	v_fmac_f32_e32 v3, v4, v3
	v_div_scale_f32 v4, vcc, 1.0, v0, 1.0
	v_mul_f32_e32 v5, v4, v3
	v_fma_f32 v6, -v2, v5, v4
	v_fmac_f32_e32 v5, v6, v3
	v_fma_f32 v2, -v2, v5, v4
	v_div_fmas_f32 v2, v2, v3, v5
	s_addc_u32 s3, s10, 0
	v_div_fixup_f32 v0, v2, v0, 1.0
	v_lshlrev_b64 v[2:3], 11, v[168:169]
	v_lshl_add_u64 v[2:3], s[2:3], 0, v[2:3]
	v_mov_b32_e32 v171, v1
	v_lshl_add_u64 v[2:3], v[2:3], 0, v[170:171]
	v_lshl_add_u64 v[2:3], v[2:3], 0, v[170:171]
	v_pk_mul_f32 v[32:33], v[32:33], v[0:1] op_sel_hi:[1,0]
	v_pk_mul_f32 v[34:35], v[34:35], v[0:1] op_sel_hi:[1,0]
	v_pk_mul_f32 v[36:37], v[36:37], v[0:1] op_sel_hi:[1,0]
	v_pk_mul_f32 v[38:39], v[38:39], v[0:1] op_sel_hi:[1,0]
	v_cvt_pk_bf16_f32 v240, v32, v33
	v_cvt_pk_bf16_f32 v241, v34, v35
	v_cvt_pk_bf16_f32 v242, v36, v37
	v_cvt_pk_bf16_f32 v243, v38, v39
	s_nop 1
	v_permlane32_swap_b32 v240, v242
	v_permlane32_swap_b32 v241, v243
	global_store_dwordx4 v[2:3], v[240:243], off offset:1024
	v_pk_mul_f32 v[40:41], v[40:41], v[0:1] op_sel_hi:[1,0]
	v_pk_mul_f32 v[42:43], v[42:43], v[0:1] op_sel_hi:[1,0]
	v_pk_mul_f32 v[44:45], v[44:45], v[0:1] op_sel_hi:[1,0]
	v_pk_mul_f32 v[46:47], v[46:47], v[0:1] op_sel_hi:[1,0]
	v_cvt_pk_bf16_f32 v240, v40, v41
	v_cvt_pk_bf16_f32 v241, v42, v43
	v_cvt_pk_bf16_f32 v242, v44, v45
	v_cvt_pk_bf16_f32 v243, v46, v47
	s_nop 1
	v_permlane32_swap_b32 v240, v242
	v_permlane32_swap_b32 v241, v243
	global_store_dwordx4 v[2:3], v[240:243], off offset:1056
	v_pk_mul_f32 v[16:17], v[16:17], v[0:1] op_sel_hi:[1,0]
	v_pk_mul_f32 v[18:19], v[18:19], v[0:1] op_sel_hi:[1,0]
	v_pk_mul_f32 v[20:21], v[20:21], v[0:1] op_sel_hi:[1,0]
	v_pk_mul_f32 v[22:23], v[22:23], v[0:1] op_sel_hi:[1,0]
	v_cvt_pk_bf16_f32 v240, v16, v17
	v_cvt_pk_bf16_f32 v241, v18, v19
	v_cvt_pk_bf16_f32 v242, v20, v21
	v_cvt_pk_bf16_f32 v243, v22, v23
	s_nop 1
	v_permlane32_swap_b32 v240, v242
	v_permlane32_swap_b32 v241, v243
	global_store_dwordx4 v[2:3], v[240:243], off offset:1088
	v_pk_mul_f32 v[24:25], v[24:25], v[0:1] op_sel_hi:[1,0]
	v_pk_mul_f32 v[26:27], v[26:27], v[0:1] op_sel_hi:[1,0]
	v_pk_mul_f32 v[28:29], v[28:29], v[0:1] op_sel_hi:[1,0]
	v_pk_mul_f32 v[30:31], v[30:31], v[0:1] op_sel_hi:[1,0]
	v_cvt_pk_bf16_f32 v240, v24, v25
	v_cvt_pk_bf16_f32 v241, v26, v27
	v_cvt_pk_bf16_f32 v242, v28, v29
	v_cvt_pk_bf16_f32 v243, v30, v31
	s_nop 1
	v_permlane32_swap_b32 v240, v242
	v_permlane32_swap_b32 v241, v243
	global_store_dwordx4 v[2:3], v[240:243], off offset:1120
	v_readlane_b32 s0, v252, 18
	v_readlane_b32 s1, v252, 19
	s_load_dword s2, s[0:1], 0x0
	s_waitcnt lgkmcnt(0)
	s_add_i32 s33, s2, s33
	s_cmpk_lt_i32 s33, 0x400
	s_cbranch_scc0 .LBB0_573

; __device__ __forceinline__ unsigned pk2(float lo, float hi) { f32x2 v = {lo, hi}; bf16x2_t b = __builtin_convertvector(v, bf16x2_t); return __builtin_bit_cast(unsigned, b); }
; __device__ __forceinline__ float shfl_xor_l(float v, int o, int lane) { return __builtin_bit_cast(float, __builtin_amdgcn_ds_bpermute((lane ^ o) << 2, __builtin_bit_cast(int, v))); }
; template <int DQK, int DV, int FLAGS, int qp, int kp, int vts, int op> ...
;     ...
;     float lt = l + shfl_xor_l(l, 32, lane);
;     if (FLAGS & AF_SINK) lt += __builtin_amdgcn_exp2f(sink2 - m);
;     const float inv = 1.0f / lt;
;     bf16* orow = O + (size_t)(32 * wave + r32) * op + 4 * hi;
; #pragma unroll
;     for (int d = 0; d < NDB; ++d)
; #pragma unroll
;         for (int g = 0; g < 4; ++g) {
;             u32x2 w; w.x = pk2(o[d][4 * g] * inv, o[d][4 * g + 1] * inv); w.y = pk2(o[d][4 * g + 2] * inv, o[d][4 * g + 3] * inv);
;             *(u32x2*)(orow + 32 * d + 8 * g) = w;
;         }
; __global__ void __launch_bounds__(NTHREADS, 2) mega_fwd(Args args) {
;     ...
;         for (int j = bid; j < 1024; j += G) {
.LBB0_575:
	ds_bpermute_b32 v0, v48, v127
	s_mov_b32 s5, 0x3fb8aa3b
	s_waitcnt vmcnt(1)
	v_fma_f32 v2, v111, s5, -v129
	v_exp_f32_e32 v2, v2
	s_lshl_b32 s4, s51, 6
	s_lshl_b64 s[40:41], s[40:41], 11
	s_waitcnt lgkmcnt(0)
	v_add_f32_e32 v0, v127, v0
	s_add_u32 s5, s74, s40
	v_add_f32_e32 v0, v2, v0
	s_addc_u32 s6, s75, s41
	v_div_scale_f32 v2, s[40:41], v0, v0, 1.0
	v_rcp_f32_e32 v3, v2
	s_lshl_b32 s4, s4, 1
	s_add_u32 s4, s5, s4
	s_addc_u32 s5, s6, 0
	v_fma_f32 v4, -v2, v3, 1.0
	v_fmac_f32_e32 v3, v4, v3
	v_div_scale_f32 v4, vcc, 1.0, v0, 1.0
	v_mul_f32_e32 v5, v4, v3
	v_fma_f32 v6, -v2, v5, v4
	v_fmac_f32_e32 v5, v6, v3
	v_fma_f32 v2, -v2, v5, v4
	v_div_fmas_f32 v2, v2, v3, v5
	v_div_fixup_f32 v0, v2, v0, 1.0
	v_lshlrev_b64 v[2:3], 11, v[108:109]
	v_lshl_add_u64 v[2:3], s[4:5], 0, v[2:3]
	v_mov_b32_e32 v111, v1
	v_lshl_add_u64 v[2:3], v[2:3], 0, v[110:111]
	v_lshl_add_u64 v[2:3], v[2:3], 0, v[110:111]
	v_pk_mul_f32 v[32:33], v[32:33], v[0:1] op_sel_hi:[1,0]
	v_pk_mul_f32 v[34:35], v[34:35], v[0:1] op_sel_hi:[1,0]
	v_pk_mul_f32 v[36:37], v[36:37], v[0:1] op_sel_hi:[1,0]
	v_pk_mul_f32 v[38:39], v[38:39], v[0:1] op_sel_hi:[1,0]
	v_cvt_pk_bf16_f32 v240, v32, v33
	v_cvt_pk_bf16_f32 v241, v34, v35
	v_cvt_pk_bf16_f32 v242, v36, v37
	v_cvt_pk_bf16_f32 v243, v38, v39
	s_nop 1
	v_permlane32_swap_b32 v240, v242
	v_permlane32_swap_b32 v241, v243
	global_store_dwordx4 v[2:3], v[240:243], off
	v_pk_mul_f32 v[40:41], v[40:41], v[0:1] op_sel_hi:[1,0]
	v_pk_mul_f32 v[42:43], v[42:43], v[0:1] op_sel_hi:[1,0]
	v_pk_mul_f32 v[44:45], v[44:45], v[0:1] op_sel_hi:[1,0]
	v_pk_mul_f32 v[46:47], v[46:47], v[0:1] op_sel_hi:[1,0]
	v_cvt_pk_bf16_f32 v240, v40, v41
	v_cvt_pk_bf16_f32 v241, v42, v43
	v_cvt_pk_bf16_f32 v242, v44, v45
	v_cvt_pk_bf16_f32 v243, v46, v47
	s_nop 1
	v_permlane32_swap_b32 v240, v242
	v_permlane32_swap_b32 v241, v243
	global_store_dwordx4 v[2:3], v[240:243], off offset:32
	v_pk_mul_f32 v[16:17], v[16:17], v[0:1] op_sel_hi:[1,0]
	v_pk_mul_f32 v[18:19], v[18:19], v[0:1] op_sel_hi:[1,0]
	v_pk_mul_f32 v[20:21], v[20:21], v[0:1] op_sel_hi:[1,0]
	v_pk_mul_f32 v[22:23], v[22:23], v[0:1] op_sel_hi:[1,0]
	v_cvt_pk_bf16_f32 v240, v16, v17
	v_cvt_pk_bf16_f32 v241, v18, v19
	v_cvt_pk_bf16_f32 v242, v20, v21
	v_cvt_pk_bf16_f32 v243, v22, v23
	s_nop 1
	v_permlane32_swap_b32 v240, v242
	v_permlane32_swap_b32 v241, v243
	global_store_dwordx4 v[2:3], v[240:243], off offset:64
	v_pk_mul_f32 v[24:25], v[24:25], v[0:1] op_sel_hi:[1,0]
	v_pk_mul_f32 v[26:27], v[26:27], v[0:1] op_sel_hi:[1,0]
	v_pk_mul_f32 v[28:29], v[28:29], v[0:1] op_sel_hi:[1,0]
	v_pk_mul_f32 v[30:31], v[30:31], v[0:1] op_sel_hi:[1,0]
	v_cvt_pk_bf16_f32 v240, v24, v25
	v_cvt_pk_bf16_f32 v241, v26, v27
	v_cvt_pk_bf16_f32 v242, v28, v29
	v_cvt_pk_bf16_f32 v243, v30, v31
	s_nop 1
	v_permlane32_swap_b32 v240, v242
	v_permlane32_swap_b32 v241, v243
	global_store_dwordx4 v[2:3], v[240:243], off offset:96
	v_readlane_b32 s4, v252, 18
	v_readlane_b32 s5, v252, 19
	s_load_dword s4, s[4:5], 0x0
	s_waitcnt lgkmcnt(0)
	s_add_i32 s50, s4, s50
	s_cmpk_lt_i32 s50, 0x400
	s_cbranch_scc0 .LBB0_594

; #define LAS __attribute__((address_space(3)))
; #define ATT_LSTORE(buf) do { LAS unsigned char* b_ = lds + (buf) * BUF; \
;         _Pragma("unroll") for (int i = 0; i < KPT; ++i) { if (KCH % NTHREADS == 0 || tid + i * NTHREADS < KCH) *(LAS u32x4*)(b_ + klo[i]) = kreg[i]; } \
;         _Pragma("unroll") for (int i = 0; i < VPT; ++i) *(LAS u32x4*)(b_ + vlo[i]) = vreg[i]; } while (0)
; template <int DQK, int DV, int FLAGS, int qp, int kp, int vts, int op> ...
;     ...
;             f32x2 rs2 = {0.f, 0.f};
; #pragma unroll
;             for (int r = 0; r < 16; ++r) { p0[r] = __builtin_amdgcn_exp2f(p0[r]); p1[r] = __builtin_amdgcn_exp2f(p1[r]); }
; #pragma unroll
;             for (int r = 0; r < 16; r += 2) { rs2 += (f32x2){p0[r], p0[r + 1]}; rs2 += (f32x2){p1[r], p1[r + 1]}; }
;             l += rs2.x + rs2.y;
;             bf16x8 pf[4];
;             pf[0] = pack_bf16x8(p0, 0); pf[1] = pack_bf16x8(p0, 8); pf[2] = pack_bf16x8(p1, 0); pf[3] = pack_bf16x8(p1, 8);
;             __builtin_amdgcn_sched_barrier(0);
; #pragma unroll
;             for (int d = 0; d < NDB; ++d) {
;                 if (d + 1 < NDB) {
; #pragma unroll
;                     for (int ks = 0; ks < 4; ++ks) vf[(d + 1) & 1][ks] = *(const LAS bf16x8*)(vb + (d + 1) * 32 * VROW + ks * 32);
;                 }
; #pragma unroll
;                 for (int ks = 0; ks < 4; ++ks) o[d] = __builtin_amdgcn_mfma_f32_32x32x16_bf16(vf[d & 1][ks], pf[ks], o[d], 0, 0, 0);
;                 __builtin_amdgcn_sched_barrier(0);
;             }
;         }
;         if (skip && more) ATT_GLOAD((FLAGS & AF_REV) ? t - 1 : t + 1);
;         if (more) ATT_LSTORE(cur ^ 1);
;         __syncthreads();
.LBB0_1281:
	v_exp_f32_e32 v116, v82
	v_exp_f32_e32 v118, v66
	v_exp_f32_e32 v117, v83
	v_exp_f32_e32 v119, v67
	v_exp_f32_e32 v120, v84
	v_exp_f32_e32 v122, v68
	v_exp_f32_e32 v121, v85
	v_exp_f32_e32 v123, v69
	v_exp_f32_e32 v124, v86
	v_exp_f32_e32 v126, v70
	v_exp_f32_e32 v125, v87
	v_exp_f32_e32 v127, v71
	v_exp_f32_e32 v128, v88
	v_exp_f32_e32 v130, v72
	v_exp_f32_e32 v129, v89
	v_exp_f32_e32 v131, v73
	v_exp_f32_e32 v132, v90
	v_exp_f32_e32 v134, v74
	v_exp_f32_e32 v133, v91
	v_exp_f32_e32 v135, v75
	v_exp_f32_e32 v136, v92
	v_exp_f32_e32 v138, v76
	v_exp_f32_e32 v137, v93
	v_exp_f32_e32 v139, v77
	v_exp_f32_e32 v140, v94
	v_exp_f32_e32 v142, v78
	v_exp_f32_e32 v141, v95
	v_exp_f32_e32 v143, v79
	v_exp_f32_e32 v144, v96
	v_exp_f32_e32 v148, v80
	v_exp_f32_e32 v145, v97
	v_exp_f32_e32 v149, v81
	s_add_u32 s2, s25, s14
	v_readlane_b32 s3, v252, 36
	s_addc_u32 s3, s3, s15
	s_add_u32 s6, s2, s37
	v_lshlrev_b64 v[114:115], 9, v[194:195]
	s_addc_u32 s7, s3, 0
	v_cvt_pk_bf16_f32 v66, v116, v117
	v_cvt_pk_bf16_f32 v67, v120, v121
	v_cvt_pk_bf16_f32 v68, v124, v125
	v_cvt_pk_bf16_f32 v69, v128, v129
	v_cvt_pk_bf16_f32 v70, v132, v133
	v_cvt_pk_bf16_f32 v71, v136, v137
	v_cvt_pk_bf16_f32 v72, v140, v141
	v_cvt_pk_bf16_f32 v73, v144, v145
	v_cvt_pk_bf16_f32 v74, v118, v119
	v_cvt_pk_bf16_f32 v75, v122, v123
	v_cvt_pk_bf16_f32 v76, v126, v127
	v_cvt_pk_bf16_f32 v77, v130, v131
	v_cvt_pk_bf16_f32 v78, v134, v135
	v_cvt_pk_bf16_f32 v79, v138, v139
	v_cvt_pk_bf16_f32 v80, v142, v143
	v_cvt_pk_bf16_f32 v81, v148, v149
	s_waitcnt lgkmcnt(3)
	v_mfma_f32_32x32x16_bf16 v[50:65], v[110:113], v[66:69], v[50:65]
	ds_read_b128 v[82:85], v0 offset:57856
	ds_read_b128 v[86:89], v0 offset:57888
	ds_read_b128 v[90:93], v0 offset:57920
	ds_read_b128 v[94:97], v0 offset:57952
	s_waitcnt lgkmcnt(6)
	v_mfma_f32_32x32x16_bf16 v[50:65], v[106:109], v[70:73], v[50:65]
	s_waitcnt lgkmcnt(5)
	v_mfma_f32_32x32x16_bf16 v[50:65], v[102:105], v[74:77], v[50:65]
	s_waitcnt lgkmcnt(4)
	v_mfma_f32_32x32x16_bf16 v[50:65], v[98:101], v[78:81], v[50:65]
	s_waitcnt lgkmcnt(3)
	v_mfma_f32_32x32x16_bf16 v[34:49], v[82:85], v[66:69], v[34:49]
	s_waitcnt lgkmcnt(2)
	v_mfma_f32_32x32x16_bf16 v[34:49], v[86:89], v[70:73], v[34:49]
	s_waitcnt lgkmcnt(1)
	v_mfma_f32_32x32x16_bf16 v[34:49], v[90:93], v[74:77], v[34:49]
	ds_read_b128 v[82:85], v0 offset:62464
	ds_read_b128 v[86:89], v0 offset:62496
	ds_read_b128 v[90:93], v0 offset:62528
	ds_read_b128 v[98:101], v0 offset:62560
	s_waitcnt lgkmcnt(4)
	v_mfma_f32_32x32x16_bf16 v[34:49], v[94:97], v[78:81], v[34:49]
	s_waitcnt lgkmcnt(3)
	v_mfma_f32_32x32x16_bf16 v[18:33], v[82:85], v[66:69], v[18:33]
	s_waitcnt lgkmcnt(2)
	v_mfma_f32_32x32x16_bf16 v[18:33], v[86:89], v[70:73], v[18:33]
	s_waitcnt lgkmcnt(1)
	v_mfma_f32_32x32x16_bf16 v[18:33], v[90:93], v[74:77], v[18:33]
	ds_read_b128 v[82:85], v211 offset:13824
	ds_read_b128 v[86:89], v211 offset:13856
	ds_read_b128 v[90:93], v211 offset:13888
	ds_read_b128 v[94:97], v211 offset:13920
	s_waitcnt lgkmcnt(4)
	v_mfma_f32_32x32x16_bf16 v[18:33], v[98:101], v[78:81], v[18:33]
	s_waitcnt lgkmcnt(3)
	v_mfma_f32_32x32x16_bf16 v[2:17], v[82:85], v[66:69], v[2:17]
	s_waitcnt lgkmcnt(2)
	v_mfma_f32_32x32x16_bf16 v[2:17], v[86:89], v[70:73], v[2:17]
	s_waitcnt lgkmcnt(1)
	v_mfma_f32_32x32x16_bf16 v[2:17], v[90:93], v[74:77], v[2:17]
	s_waitcnt lgkmcnt(0)
	v_mfma_f32_32x32x16_bf16 v[2:17], v[94:97], v[78:81], v[2:17]
	v_add_f32_e64 v66, v116, 0
	v_add_f32_e64 v67, v117, 0
	v_add_f32_e64 v66, v118, v66
	v_add_f32_e64 v67, v119, v67
	s_barrier
; #define LAS __attribute__((address_space(3)))
; __device__ __forceinline__ unsigned pk2(float lo, float hi) { f32x2 v = {lo, hi}; bf16x2_t b = __builtin_convertvector(v, bf16x2_t); return __builtin_bit_cast(unsigned, b); }
; __device__ __forceinline__ float shfl_xor_l(float v, int o, int lane) { return __builtin_bit_cast(float, __builtin_amdgcn_ds_bpermute((lane ^ o) << 2, __builtin_bit_cast(int, v))); }
; template <int DQK, int DV, int FLAGS, int qp, int kp, int vts, int op> ...
;     ...
;             f32x2 rs2 = {0.f, 0.f};
; #pragma unroll
;             for (int r = 0; r < 16; ++r) { p0[r] = __builtin_amdgcn_exp2f(p0[r]); p1[r] = __builtin_amdgcn_exp2f(p1[r]); }
; #pragma unroll
;             for (int r = 0; r < 16; r += 2) { rs2 += (f32x2){p0[r], p0[r + 1]}; rs2 += (f32x2){p1[r], p1[r + 1]}; }
;             l += rs2.x + rs2.y;
;             bf16x8 pf[4];
;             pf[0] = pack_bf16x8(p0, 0); pf[1] = pack_bf16x8(p0, 8); pf[2] = pack_bf16x8(p1, 0); pf[3] = pack_bf16x8(p1, 8);
;             __builtin_amdgcn_sched_barrier(0);
; #pragma unroll
;             for (int d = 0; d < NDB; ++d) {
;                 if (d + 1 < NDB) {
; #pragma unroll
;                     for (int ks = 0; ks < 4; ++ks) vf[(d + 1) & 1][ks] = *(const LAS bf16x8*)(vb + (d + 1) * 32 * VROW + ks * 32);
;                 }
; #pragma unroll
;                 for (int ks = 0; ks < 4; ++ks) o[d] = __builtin_amdgcn_mfma_f32_32x32x16_bf16(vf[d & 1][ks], pf[ks], o[d], 0, 0, 0);
;                 __builtin_amdgcn_sched_barrier(0);
;             }
;         }
;         if (skip && more) ATT_GLOAD((FLAGS & AF_REV) ? t - 1 : t + 1);
;         if (more) ATT_LSTORE(cur ^ 1);
;         __syncthreads();
;     }
;     ...
;     float lt = l + shfl_xor_l(l, 32, lane);
;     if (FLAGS & AF_SINK) lt += __builtin_amdgcn_exp2f(sink2 - m);
;     const float inv = 1.0f / lt;
;     bf16* orow = O + (size_t)(32 * wave + r32) * op + 4 * hi;
; #pragma unroll
;     for (int d = 0; d < NDB; ++d)
; #pragma unroll
;         for (int g = 0; g < 4; ++g) {
;             u32x2 w; w.x = pk2(o[d][4 * g] * inv, o[d][4 * g + 1] * inv); w.y = pk2(o[d][4 * g + 2] * inv, o[d][4 * g + 3] * inv);
;             *(u32x2*)(orow + 32 * d + 8 * g) = w;
;         }
	v_pk_add_f32 v[66:67], v[120:121], v[66:67]
	s_nop 0
	v_pk_add_f32 v[66:67], v[122:123], v[66:67]
	s_nop 0
	v_pk_add_f32 v[66:67], v[124:125], v[66:67]
	s_nop 0
	v_pk_add_f32 v[66:67], v[126:127], v[66:67]
	s_nop 0
	v_pk_add_f32 v[66:67], v[128:129], v[66:67]
	s_nop 0
	v_pk_add_f32 v[66:67], v[130:131], v[66:67]
	s_nop 0
	v_pk_add_f32 v[66:67], v[132:133], v[66:67]
	s_nop 0
	v_pk_add_f32 v[66:67], v[134:135], v[66:67]
	s_nop 0
	v_pk_add_f32 v[66:67], v[136:137], v[66:67]
	s_nop 0
	v_pk_add_f32 v[66:67], v[138:139], v[66:67]
	s_nop 0
	v_pk_add_f32 v[66:67], v[140:141], v[66:67]
	s_nop 0
	v_pk_add_f32 v[66:67], v[142:143], v[66:67]
	s_nop 0
	v_pk_add_f32 v[66:67], v[144:145], v[66:67]
	s_nop 0
	v_pk_add_f32 v[66:67], v[148:149], v[66:67]
	s_nop 0
	v_add_f32_e32 v0, v66, v67
	v_add_f32_e32 v0, v146, v0
	ds_bpermute_b32 v66, v205, v0
	s_waitcnt lgkmcnt(0)
	v_add_f32_e32 v0, v0, v66
	v_div_scale_f32 v66, s[2:3], v0, v0, 1.0
	v_rcp_f32_e32 v67, v66
	v_div_scale_f32 v68, vcc, 1.0, v0, 1.0
	v_readlane_b32 s2, v252, 18
	v_fma_f32 v69, -v66, v67, 1.0
	v_fmac_f32_e32 v67, v69, v67
	v_mul_f32_e32 v69, v68, v67
	v_fma_f32 v70, -v66, v69, v68
	v_fmac_f32_e32 v69, v70, v67
	v_fma_f32 v66, -v66, v69, v68
	v_div_fmas_f32 v66, v66, v67, v69
	v_div_fixup_f32 v66, v66, v0, 1.0
	v_lshl_add_u64 v[68:69], v[114:115], 1, s[6:7]
	v_lshlrev_b32_e32 v0, 3, v204
	v_lshl_add_u64 v[68:69], v[68:69], 0, v[0:1]
	v_lshl_add_u64 v[68:69], v[68:69], 0, v[0:1]
	v_pk_mul_f32 v[50:51], v[50:51], v[66:67] op_sel_hi:[1,0]
	v_pk_mul_f32 v[52:53], v[52:53], v[66:67] op_sel_hi:[1,0]
	v_pk_mul_f32 v[54:55], v[54:55], v[66:67] op_sel_hi:[1,0]
	v_pk_mul_f32 v[56:57], v[56:57], v[66:67] op_sel_hi:[1,0]
	v_cvt_pk_bf16_f32 v240, v50, v51
	v_cvt_pk_bf16_f32 v241, v52, v53
	v_cvt_pk_bf16_f32 v242, v54, v55
	v_cvt_pk_bf16_f32 v243, v56, v57
	s_nop 1
	v_permlane32_swap_b32 v240, v242
	v_permlane32_swap_b32 v241, v243
	global_store_dwordx4 v[68:69], v[240:243], off
	v_pk_mul_f32 v[58:59], v[58:59], v[66:67] op_sel_hi:[1,0]
	v_pk_mul_f32 v[60:61], v[60:61], v[66:67] op_sel_hi:[1,0]
	v_pk_mul_f32 v[62:63], v[62:63], v[66:67] op_sel_hi:[1,0]
	v_pk_mul_f32 v[64:65], v[64:65], v[66:67] op_sel_hi:[1,0]
	v_cvt_pk_bf16_f32 v240, v58, v59
	v_cvt_pk_bf16_f32 v241, v60, v61
	v_cvt_pk_bf16_f32 v242, v62, v63
	v_cvt_pk_bf16_f32 v243, v64, v65
	s_nop 1
	v_permlane32_swap_b32 v240, v242
	v_permlane32_swap_b32 v241, v243
	global_store_dwordx4 v[68:69], v[240:243], off offset:32
	v_pk_mul_f32 v[34:35], v[34:35], v[66:67] op_sel_hi:[1,0]
	v_pk_mul_f32 v[36:37], v[36:37], v[66:67] op_sel_hi:[1,0]
	v_pk_mul_f32 v[38:39], v[38:39], v[66:67] op_sel_hi:[1,0]
	v_pk_mul_f32 v[40:41], v[40:41], v[66:67] op_sel_hi:[1,0]
	v_cvt_pk_bf16_f32 v240, v34, v35
	v_cvt_pk_bf16_f32 v241, v36, v37
	v_cvt_pk_bf16_f32 v242, v38, v39
	v_cvt_pk_bf16_f32 v243, v40, v41
	s_nop 1
	v_permlane32_swap_b32 v240, v242
	v_permlane32_swap_b32 v241, v243
	global_store_dwordx4 v[68:69], v[240:243], off offset:64
	v_pk_mul_f32 v[42:43], v[42:43], v[66:67] op_sel_hi:[1,0]
	v_pk_mul_f32 v[44:45], v[44:45], v[66:67] op_sel_hi:[1,0]
	v_pk_mul_f32 v[46:47], v[46:47], v[66:67] op_sel_hi:[1,0]
	v_pk_mul_f32 v[48:49], v[48:49], v[66:67] op_sel_hi:[1,0]
	v_cvt_pk_bf16_f32 v240, v42, v43
	v_cvt_pk_bf16_f32 v241, v44, v45
	v_cvt_pk_bf16_f32 v242, v46, v47
	v_cvt_pk_bf16_f32 v243, v48, v49
	s_nop 1
	v_permlane32_swap_b32 v240, v242
	v_permlane32_swap_b32 v241, v243
	global_store_dwordx4 v[68:69], v[240:243], off offset:96
	v_pk_mul_f32 v[18:19], v[18:19], v[66:67] op_sel_hi:[1,0]
	v_pk_mul_f32 v[20:21], v[20:21], v[66:67] op_sel_hi:[1,0]
	v_pk_mul_f32 v[22:23], v[22:23], v[66:67] op_sel_hi:[1,0]
	v_pk_mul_f32 v[24:25], v[24:25], v[66:67] op_sel_hi:[1,0]
	v_cvt_pk_bf16_f32 v240, v18, v19
	v_cvt_pk_bf16_f32 v241, v20, v21
	v_cvt_pk_bf16_f32 v242, v22, v23
	v_cvt_pk_bf16_f32 v243, v24, v25
	s_nop 1
	v_permlane32_swap_b32 v240, v242
	v_permlane32_swap_b32 v241, v243
	global_store_dwordx4 v[68:69], v[240:243], off offset:128
	v_pk_mul_f32 v[26:27], v[26:27], v[66:67] op_sel_hi:[1,0]
	v_pk_mul_f32 v[28:29], v[28:29], v[66:67] op_sel_hi:[1,0]
	v_pk_mul_f32 v[30:31], v[30:31], v[66:67] op_sel_hi:[1,0]
	v_pk_mul_f32 v[32:33], v[32:33], v[66:67] op_sel_hi:[1,0]
	v_cvt_pk_bf16_f32 v240, v26, v27
	v_cvt_pk_bf16_f32 v241, v28, v29
	v_cvt_pk_bf16_f32 v242, v30, v31
	v_cvt_pk_bf16_f32 v243, v32, v33
	s_nop 1
	v_permlane32_swap_b32 v240, v242
	v_permlane32_swap_b32 v241, v243
	global_store_dwordx4 v[68:69], v[240:243], off offset:160
	v_pk_mul_f32 v[2:3], v[2:3], v[66:67] op_sel_hi:[1,0]
	v_pk_mul_f32 v[4:5], v[4:5], v[66:67] op_sel_hi:[1,0]
	v_pk_mul_f32 v[6:7], v[6:7], v[66:67] op_sel_hi:[1,0]
	v_pk_mul_f32 v[8:9], v[8:9], v[66:67] op_sel_hi:[1,0]
	v_cvt_pk_bf16_f32 v240, v2, v3
	v_cvt_pk_bf16_f32 v241, v4, v5
	v_cvt_pk_bf16_f32 v242, v6, v7
	v_cvt_pk_bf16_f32 v243, v8, v9
	s_nop 1
	v_permlane32_swap_b32 v240, v242
	v_permlane32_swap_b32 v241, v243
	global_store_dwordx4 v[68:69], v[240:243], off offset:192
	v_pk_mul_f32 v[10:11], v[10:11], v[66:67] op_sel_hi:[1,0]
	v_pk_mul_f32 v[12:13], v[12:13], v[66:67] op_sel_hi:[1,0]
	v_pk_mul_f32 v[14:15], v[14:15], v[66:67] op_sel_hi:[1,0]
	v_pk_mul_f32 v[16:17], v[16:17], v[66:67] op_sel_hi:[1,0]
	v_cvt_pk_bf16_f32 v240, v10, v11
	v_cvt_pk_bf16_f32 v241, v12, v13
	v_cvt_pk_bf16_f32 v242, v14, v15
	v_cvt_pk_bf16_f32 v243, v16, v17
	s_nop 1
	v_permlane32_swap_b32 v240, v242
	v_permlane32_swap_b32 v241, v243
	global_store_dwordx4 v[68:69], v[240:243], off offset:224
	v_readlane_b32 s3, v252, 19
	s_load_dword s2, s[2:3], 0x0
	s_waitcnt lgkmcnt(0)
	s_add_i32 s36, s2, s36
	s_cmpk_lt_i32 s36, 0x200
	s_cbranch_scc0 .LBB0_1288
